# deferred copies in the scan phase issued with the non-temporal cache hint (keep the scan's records cache-resident), otherwise as v61
# speedup vs baseline: 1.0082x; 1.0082x over previous
; #define LAS __attribute__((address_space(3)))
; __device__ __forceinline__ void transpose_item(const float* W, int K, int N, bf16_t* WT, LAS float* scr, int item, int lane) {
;     const int nblk = (N + 31) / 32, kb = item / nblk, nb = item % nblk, k0 = 64 * kb, n0 = 32 * nb;
;     const int nn = n0 + (lane & 31); const bool ok = nn < N;
;     float v[32];
; #pragma unroll
;     for (int i = 0; i < 32; ++i) { const int kk = 2 * i + (lane >> 5); v[i] = ok ? W[(size_t)(k0 + kk) * N + nn] : 0.f; }
; #pragma unroll
;     for (int i = 0; i < 32; ++i) { const int kk = 2 * i + (lane >> 5); scr[kk * 33 + (lane & 31)] = v[i]; }
.Lp4t_la_p0_done:
	v_mad_u32_u24 v58, v0, s19, v2
	v_mad_u32_u24 v59, v0, s19, v3
	v_mad_u32_u24 v60, v0, s19, v4
	v_mad_u32_u24 v61, v0, s19, v5
	s_mov_b64 exec, s[34:35]
	s_mov_b32 m0, s6
	s_nop 0
	global_load_lds_dword v58, s[28:29] nt
	s_add_i32 m0, m0, 0x100
	s_add_u32 s28, s28, s32
	s_addc_u32 s29, s29, 0
	global_load_lds_dword v58, s[28:29] nt
	s_add_i32 m0, m0, 0x100
	s_add_u32 s28, s28, s32
	s_addc_u32 s29, s29, 0
	global_load_lds_dword v58, s[28:29] nt
	s_add_i32 m0, m0, 0x100
	s_add_u32 s28, s28, s32
	s_addc_u32 s29, s29, 0
	global_load_lds_dword v58, s[28:29] nt
	s_mov_b64 exec, s[34:35]
	s_add_i32 m0, m0, 0x100
	s_add_u32 s28, s28, s32
	s_addc_u32 s29, s29, 0
	global_load_lds_dword v59, s[28:29] nt
	s_add_i32 m0, m0, 0x100
	s_add_u32 s28, s28, s32
	s_addc_u32 s29, s29, 0
	global_load_lds_dword v59, s[28:29] nt
	s_add_i32 m0, m0, 0x100
	s_add_u32 s28, s28, s32
	s_addc_u32 s29, s29, 0
	global_load_lds_dword v59, s[28:29] nt
	s_add_i32 m0, m0, 0x100
	s_add_u32 s28, s28, s32
	s_addc_u32 s29, s29, 0
	global_load_lds_dword v59, s[28:29] nt
	s_mov_b64 exec, s[36:37]
	s_add_i32 m0, m0, 0x100
	s_add_u32 s28, s28, s32
	s_addc_u32 s29, s29, 0
	global_load_lds_dword v60, s[28:29] nt
	s_add_i32 m0, m0, 0x100
	s_add_u32 s28, s28, s32
	s_addc_u32 s29, s29, 0
	global_load_lds_dword v60, s[28:29] nt
	s_add_i32 m0, m0, 0x100
	s_add_u32 s28, s28, s32
	s_addc_u32 s29, s29, 0
	global_load_lds_dword v60, s[28:29] nt
	s_add_i32 m0, m0, 0x100
	s_add_u32 s28, s28, s32
	s_addc_u32 s29, s29, 0
	global_load_lds_dword v60, s[28:29] nt
	s_mov_b64 exec, s[36:37]
	s_add_i32 m0, m0, 0x100
	s_add_u32 s28, s28, s32
	s_addc_u32 s29, s29, 0
	global_load_lds_dword v61, s[28:29] nt
	s_add_i32 m0, m0, 0x100
	s_add_u32 s28, s28, s32
	s_addc_u32 s29, s29, 0
	global_load_lds_dword v61, s[28:29] nt
	s_add_i32 m0, m0, 0x100
	s_add_u32 s28, s28, s32
	s_addc_u32 s29, s29, 0
	global_load_lds_dword v61, s[28:29] nt
	s_add_i32 m0, m0, 0x100
	s_add_u32 s28, s28, s32
	s_addc_u32 s29, s29, 0
	global_load_lds_dword v61, s[28:29] nt
	s_mov_b64 exec, s[34:35]
	s_add_i32 m0, m0, 0x100
	s_add_u32 s28, s28, s32
	s_addc_u32 s29, s29, 0
	global_load_lds_dword v58, s[28:29] nt
	s_add_i32 m0, m0, 0x100
	s_add_u32 s28, s28, s32
	s_addc_u32 s29, s29, 0
	global_load_lds_dword v58, s[28:29] nt
	s_add_i32 m0, m0, 0x100
	s_add_u32 s28, s28, s32
	s_addc_u32 s29, s29, 0
	global_load_lds_dword v58, s[28:29] nt
	s_add_i32 m0, m0, 0x100
	s_add_u32 s28, s28, s32
	s_addc_u32 s29, s29, 0
	global_load_lds_dword v58, s[28:29] nt
	s_mov_b64 exec, s[34:35]
	s_add_i32 m0, m0, 0x100
	s_add_u32 s28, s28, s32
	s_addc_u32 s29, s29, 0
	global_load_lds_dword v59, s[28:29] nt
	s_add_i32 m0, m0, 0x100
	s_add_u32 s28, s28, s32
	s_addc_u32 s29, s29, 0
	global_load_lds_dword v59, s[28:29] nt
	s_add_i32 m0, m0, 0x100
	s_add_u32 s28, s28, s32
	s_addc_u32 s29, s29, 0
	global_load_lds_dword v59, s[28:29] nt
	s_add_i32 m0, m0, 0x100
	s_add_u32 s28, s28, s32
	s_addc_u32 s29, s29, 0
	global_load_lds_dword v59, s[28:29] nt
	s_mov_b64 exec, s[36:37]
	s_add_i32 m0, m0, 0x100
	s_add_u32 s28, s28, s32
	s_addc_u32 s29, s29, 0
	global_load_lds_dword v60, s[28:29] nt
	s_add_i32 m0, m0, 0x100
	s_add_u32 s28, s28, s32
	s_addc_u32 s29, s29, 0
	global_load_lds_dword v60, s[28:29] nt
	s_add_i32 m0, m0, 0x100
	s_add_u32 s28, s28, s32
	s_addc_u32 s29, s29, 0
	global_load_lds_dword v60, s[28:29] nt
	s_add_i32 m0, m0, 0x100
	s_add_u32 s28, s28, s32
	s_addc_u32 s29, s29, 0
	global_load_lds_dword v60, s[28:29] nt
	s_mov_b64 exec, s[36:37]
	s_add_i32 m0, m0, 0x100
	s_add_u32 s28, s28, s32
	s_addc_u32 s29, s29, 0
	global_load_lds_dword v61, s[28:29] nt
	s_add_i32 m0, m0, 0x100
	s_add_u32 s28, s28, s32
	s_addc_u32 s29, s29, 0
	global_load_lds_dword v61, s[28:29] nt
	s_add_i32 m0, m0, 0x100
	s_add_u32 s28, s28, s32
	s_addc_u32 s29, s29, 0
	global_load_lds_dword v61, s[28:29] nt
	s_add_i32 m0, m0, 0x100
	s_add_u32 s28, s28, s32
	s_addc_u32 s29, s29, 0
	global_load_lds_dword v61, s[28:29] nt
	s_mov_b64 exec, -1
	s_add_i32 s5, s4, s18
	s_cmp_lt_i32 s5, s16
	s_cbranch_scc0 .Lp4t_nopf1
	s_mov_b32 s7, s5
	s_cmp_ge_u32 s7, 0x2020
	s_cselect_b32 s70, s99, s98
	s_add_u32 s7, s7, s70
	s_cmp_ge_u32 s7, 0x8080
	s_cbranch_scc1 .Lp4t_la_p1_out
	s_mul_hi_u32 s38, s7, 0x7f808
	s_mul_i32 s70, s38, 0x2020
	s_sub_u32 s7, s7, s70
	s_mul_hi_u32 s55, s7, 0xff0100
	s_mul_i32 s70, s55, 0x101
	s_sub_u32 s7, s7, s70
	s_mul_i32 s70, s38, 0x4020000
	s_mul_i32 s71, s55, 0x201000
	s_add_u32 s70, s70, s71
	s_lshl_b32 s71, s7, 7
	s_add_u32 s70, s70, s71
	s_add_u32 s28, s22, s70
	s_addc_u32 s29, s23, 0
	s_mov_b32 s19, 0x8040
	s_mov_b32 s32, 0x10080
	s_mov_b64 s[34:35], -1
	s_mov_b64 s[36:37], -1
	s_cmp_eq_u32 s7, 0x100
	s_cbranch_scc0 .Lp4t_la_p1_done
	s_mov_b32 s34, 0xffff
	s_mov_b32 s35, 0xffff
	s_mov_b32 s36, 0xffff0000
	s_mov_b32 s37, 0xffff0000
	s_branch .Lp4t_la_p1_done

; #define LAS __attribute__((address_space(3)))
; __device__ __forceinline__ void transpose_item(const float* W, int K, int N, bf16_t* WT, LAS float* scr, int item, int lane) {
;     const int nblk = (N + 31) / 32, kb = item / nblk, nb = item % nblk, k0 = 64 * kb, n0 = 32 * nb;
;     const int nn = n0 + (lane & 31); const bool ok = nn < N;
;     float v[32];
; #pragma unroll
;     for (int i = 0; i < 32; ++i) { const int kk = 2 * i + (lane >> 5); v[i] = ok ? W[(size_t)(k0 + kk) * N + nn] : 0.f; }
; #pragma unroll
;     for (int i = 0; i < 32; ++i) { const int kk = 2 * i + (lane >> 5); scr[kk * 33 + (lane & 31)] = v[i]; }
.Lp4t_la_p1_done:
	v_mad_u32_u24 v58, v0, s19, v2
	v_mad_u32_u24 v59, v0, s19, v3
	v_mad_u32_u24 v60, v0, s19, v4
	v_mad_u32_u24 v61, v0, s19, v5
	s_mov_b64 exec, s[34:35]
	s_xor_b32 m0, s6, 0x2000
	s_nop 0
	global_load_lds_dword v58, s[28:29] nt
	s_add_i32 m0, m0, 0x100
	s_add_u32 s28, s28, s32
	s_addc_u32 s29, s29, 0
	global_load_lds_dword v58, s[28:29] nt
	s_add_i32 m0, m0, 0x100
	s_add_u32 s28, s28, s32
	s_addc_u32 s29, s29, 0
	global_load_lds_dword v58, s[28:29] nt
	s_add_i32 m0, m0, 0x100
	s_add_u32 s28, s28, s32
	s_addc_u32 s29, s29, 0
	global_load_lds_dword v58, s[28:29] nt
	s_mov_b64 exec, s[34:35]
	s_add_i32 m0, m0, 0x100
	s_add_u32 s28, s28, s32
	s_addc_u32 s29, s29, 0
	global_load_lds_dword v59, s[28:29] nt
	s_add_i32 m0, m0, 0x100
	s_add_u32 s28, s28, s32
	s_addc_u32 s29, s29, 0
	global_load_lds_dword v59, s[28:29] nt
	s_add_i32 m0, m0, 0x100
	s_add_u32 s28, s28, s32
	s_addc_u32 s29, s29, 0
	global_load_lds_dword v59, s[28:29] nt
	s_add_i32 m0, m0, 0x100
	s_add_u32 s28, s28, s32
	s_addc_u32 s29, s29, 0
	global_load_lds_dword v59, s[28:29] nt
	s_mov_b64 exec, s[36:37]
	s_add_i32 m0, m0, 0x100
	s_add_u32 s28, s28, s32
	s_addc_u32 s29, s29, 0
	global_load_lds_dword v60, s[28:29] nt
	s_add_i32 m0, m0, 0x100
	s_add_u32 s28, s28, s32
	s_addc_u32 s29, s29, 0
	global_load_lds_dword v60, s[28:29] nt
	s_add_i32 m0, m0, 0x100
	s_add_u32 s28, s28, s32
	s_addc_u32 s29, s29, 0
	global_load_lds_dword v60, s[28:29] nt
	s_add_i32 m0, m0, 0x100
	s_add_u32 s28, s28, s32
	s_addc_u32 s29, s29, 0
	global_load_lds_dword v60, s[28:29] nt
	s_mov_b64 exec, s[36:37]
	s_add_i32 m0, m0, 0x100
	s_add_u32 s28, s28, s32
	s_addc_u32 s29, s29, 0
	global_load_lds_dword v61, s[28:29] nt
	s_add_i32 m0, m0, 0x100
	s_add_u32 s28, s28, s32
	s_addc_u32 s29, s29, 0
	global_load_lds_dword v61, s[28:29] nt
	s_add_i32 m0, m0, 0x100
	s_add_u32 s28, s28, s32
	s_addc_u32 s29, s29, 0
	global_load_lds_dword v61, s[28:29] nt
	s_add_i32 m0, m0, 0x100
	s_add_u32 s28, s28, s32
	s_addc_u32 s29, s29, 0
	global_load_lds_dword v61, s[28:29] nt
	s_mov_b64 exec, s[34:35]
	s_add_i32 m0, m0, 0x100
	s_add_u32 s28, s28, s32
	s_addc_u32 s29, s29, 0
	global_load_lds_dword v58, s[28:29] nt
	s_add_i32 m0, m0, 0x100
	s_add_u32 s28, s28, s32
	s_addc_u32 s29, s29, 0
	global_load_lds_dword v58, s[28:29] nt
	s_add_i32 m0, m0, 0x100
	s_add_u32 s28, s28, s32
	s_addc_u32 s29, s29, 0
	global_load_lds_dword v58, s[28:29] nt
	s_add_i32 m0, m0, 0x100
	s_add_u32 s28, s28, s32
	s_addc_u32 s29, s29, 0
	global_load_lds_dword v58, s[28:29] nt
	s_mov_b64 exec, s[34:35]
	s_add_i32 m0, m0, 0x100
	s_add_u32 s28, s28, s32
	s_addc_u32 s29, s29, 0
	global_load_lds_dword v59, s[28:29] nt
	s_add_i32 m0, m0, 0x100
	s_add_u32 s28, s28, s32
	s_addc_u32 s29, s29, 0
	global_load_lds_dword v59, s[28:29] nt
	s_add_i32 m0, m0, 0x100
	s_add_u32 s28, s28, s32
	s_addc_u32 s29, s29, 0
	global_load_lds_dword v59, s[28:29] nt
	s_add_i32 m0, m0, 0x100
	s_add_u32 s28, s28, s32
	s_addc_u32 s29, s29, 0
	global_load_lds_dword v59, s[28:29] nt
	s_mov_b64 exec, s[36:37]
	s_add_i32 m0, m0, 0x100
	s_add_u32 s28, s28, s32
	s_addc_u32 s29, s29, 0
	global_load_lds_dword v60, s[28:29] nt
	s_add_i32 m0, m0, 0x100
	s_add_u32 s28, s28, s32
	s_addc_u32 s29, s29, 0
	global_load_lds_dword v60, s[28:29] nt
	s_add_i32 m0, m0, 0x100
	s_add_u32 s28, s28, s32
	s_addc_u32 s29, s29, 0
	global_load_lds_dword v60, s[28:29] nt
	s_add_i32 m0, m0, 0x100
	s_add_u32 s28, s28, s32
	s_addc_u32 s29, s29, 0
	global_load_lds_dword v60, s[28:29] nt
	s_mov_b64 exec, s[36:37]
	s_add_i32 m0, m0, 0x100
	s_add_u32 s28, s28, s32
	s_addc_u32 s29, s29, 0
	global_load_lds_dword v61, s[28:29] nt
	s_add_i32 m0, m0, 0x100
	s_add_u32 s28, s28, s32
	s_addc_u32 s29, s29, 0
	global_load_lds_dword v61, s[28:29] nt
	s_add_i32 m0, m0, 0x100
	s_add_u32 s28, s28, s32
	s_addc_u32 s29, s29, 0
	global_load_lds_dword v61, s[28:29] nt
	s_add_i32 m0, m0, 0x100
	s_add_u32 s28, s28, s32
	s_addc_u32 s29, s29, 0
	global_load_lds_dword v61, s[28:29] nt
	s_mov_b64 exec, -1

; #define LAS __attribute__((address_space(3)))
; __device__ __forceinline__ unsigned pk2(float lo, float hi) { return pg8::cvt_pk_bf16(lo, hi); }
; #define LDS_WAIT() asm volatile("s_waitcnt lgkmcnt(0)" ::: "memory")
; __device__ __forceinline__ void transpose_item(const float* W, int K, int N, bf16_t* WT, LAS float* scr, int item, int lane) {
;     const int nblk = (N + 31) / 32, kb = item / nblk, nb = item % nblk, k0 = 64 * kb, n0 = 32 * nb;
;     const int nn = n0 + (lane & 31); const bool ok = nn < N;
;     float v[32];
; #pragma unroll
;     for (int i = 0; i < 32; ++i) { const int kk = 2 * i + (lane >> 5); v[i] = ok ? W[(size_t)(k0 + kk) * N + nn] : 0.f; }
; #pragma unroll
;     for (int i = 0; i < 32; ++i) { const int kk = 2 * i + (lane >> 5); scr[kk * 33 + (lane & 31)] = v[i]; }
;     LDS_WAIT(); asm volatile("" ::: "memory");
;     const int c = lane & 7;
; #pragma unroll
;     for (int j = 0; j < 4; ++j) { const int n = (lane >> 3) + 8 * j; const LAS float* s = scr + (8 * c) * 33 + n;
;         u32x4 o; o.x = pk2(s[0 * 33], s[1 * 33]); o.y = pk2(s[2 * 33], s[3 * 33]); o.z = pk2(s[4 * 33], s[5 * 33]); o.w = pk2(s[6 * 33], s[7 * 33]);
;         *(u32x4*)(WT + (size_t)(n0 + n) * K + k0 + 8 * c) = o; }
.Lp4t_wd:
	ds_read2_b32 v[18:19], v62 offset0:0 offset1:32
	ds_read2_b32 v[20:21], v62 offset0:64 offset1:96
	ds_read2_b32 v[22:23], v62 offset0:128 offset1:160
	ds_read2_b32 v[24:25], v62 offset0:192 offset1:224
	ds_read2_b32 v[26:27], v63 offset0:0 offset1:32
	ds_read2_b32 v[28:29], v63 offset0:64 offset1:96
	ds_read2_b32 v[30:31], v63 offset0:128 offset1:160
	ds_read2_b32 v[32:33], v63 offset0:192 offset1:224
	ds_read2_b32 v[34:35], v64 offset0:0 offset1:32
	ds_read2_b32 v[36:37], v64 offset0:64 offset1:96
	ds_read2_b32 v[38:39], v64 offset0:128 offset1:160
	ds_read2_b32 v[40:41], v64 offset0:192 offset1:224
	ds_read2_b32 v[42:43], v65 offset0:0 offset1:32
	ds_read2_b32 v[44:45], v65 offset0:64 offset1:96
	ds_read2_b32 v[46:47], v65 offset0:128 offset1:160
	ds_read2_b32 v[48:49], v65 offset0:192 offset1:224
	s_waitcnt lgkmcnt(12)
	v_cvt_pk_bf16_f32 v50, v18, v19
	v_cvt_pk_bf16_f32 v51, v20, v21
	v_cvt_pk_bf16_f32 v52, v22, v23
	v_cvt_pk_bf16_f32 v53, v24, v25
	global_store_dwordx4 v13, v[50:53], s[30:31] nt
	s_waitcnt lgkmcnt(8)
	v_cvt_pk_bf16_f32 v54, v26, v27
	v_cvt_pk_bf16_f32 v55, v28, v29
	v_cvt_pk_bf16_f32 v56, v30, v31
	v_cvt_pk_bf16_f32 v57, v32, v33
	global_store_dwordx4 v14, v[54:57], s[30:31] nt
	s_waitcnt lgkmcnt(4)
	v_cvt_pk_bf16_f32 v50, v34, v35
	v_cvt_pk_bf16_f32 v51, v36, v37
	v_cvt_pk_bf16_f32 v52, v38, v39
	v_cvt_pk_bf16_f32 v53, v40, v41
	v_cndmask_b32_e64 v50, v50, 0, s[48:49]
	v_cndmask_b32_e64 v51, v51, 0, s[48:49]
	v_cndmask_b32_e64 v52, v52, 0, s[48:49]
	v_cndmask_b32_e64 v53, v53, 0, s[48:49]
	global_store_dwordx4 v15, v[50:53], s[30:31] nt
	s_waitcnt lgkmcnt(0)
	v_cvt_pk_bf16_f32 v54, v42, v43
	v_cvt_pk_bf16_f32 v55, v44, v45
	v_cvt_pk_bf16_f32 v56, v46, v47
	v_cvt_pk_bf16_f32 v57, v48, v49
	v_cndmask_b32_e64 v54, v54, 0, s[48:49]
	v_cndmask_b32_e64 v55, v55, 0, s[48:49]
	v_cndmask_b32_e64 v56, v56, 0, s[48:49]
	v_cndmask_b32_e64 v57, v57, 0, s[48:49]
	global_store_dwordx4 v16, v[54:57], s[30:31] nt
	s_cmp_lt_i32 s5, s16
	s_cbranch_scc0 .Lp4t_nopf
	s_mov_b32 s7, s5
	s_cmp_ge_u32 s7, 0x2020
	s_cselect_b32 s70, s99, s98
	s_add_u32 s7, s7, s70
	s_cmp_ge_u32 s7, 0x8080
	s_cbranch_scc1 .Lp4t_la_lp_out
	s_mul_hi_u32 s38, s7, 0x7f808
	s_mul_i32 s70, s38, 0x2020
	s_sub_u32 s7, s7, s70
	s_mul_hi_u32 s55, s7, 0xff0100
	s_mul_i32 s70, s55, 0x101
	s_sub_u32 s7, s7, s70
	s_mul_i32 s70, s38, 0x4020000
	s_mul_i32 s71, s55, 0x201000
	s_add_u32 s70, s70, s71
	s_lshl_b32 s71, s7, 7
	s_add_u32 s70, s70, s71
	s_add_u32 s28, s22, s70
	s_addc_u32 s29, s23, 0
	s_mov_b32 s19, 0x8040
	s_mov_b32 s32, 0x10080
	s_mov_b64 s[34:35], -1
	s_mov_b64 s[36:37], -1
	s_cmp_eq_u32 s7, 0x100
	s_cbranch_scc0 .Lp4t_la_lp_done
	s_mov_b32 s34, 0xffff
	s_mov_b32 s35, 0xffff
	s_mov_b32 s36, 0xffff0000
	s_mov_b32 s37, 0xffff0000
	s_branch .Lp4t_la_lp_done

; #define LAS __attribute__((address_space(3)))
; __device__ __forceinline__ void transpose_item(const float* W, int K, int N, bf16_t* WT, LAS float* scr, int item, int lane) {
;     const int nblk = (N + 31) / 32, kb = item / nblk, nb = item % nblk, k0 = 64 * kb, n0 = 32 * nb;
;     const int nn = n0 + (lane & 31); const bool ok = nn < N;
;     float v[32];
; #pragma unroll
;     for (int i = 0; i < 32; ++i) { const int kk = 2 * i + (lane >> 5); v[i] = ok ? W[(size_t)(k0 + kk) * N + nn] : 0.f; }
; #pragma unroll
;     for (int i = 0; i < 32; ++i) { const int kk = 2 * i + (lane >> 5); scr[kk * 33 + (lane & 31)] = v[i]; }
.Lp4t_la_lp_done:
	v_mad_u32_u24 v58, v0, s19, v2
	v_mad_u32_u24 v59, v0, s19, v3
	v_mad_u32_u24 v60, v0, s19, v4
	v_mad_u32_u24 v61, v0, s19, v5
	s_mov_b64 exec, s[34:35]
	s_mov_b32 m0, s6
	s_nop 0
	global_load_lds_dword v58, s[28:29] nt
	s_add_i32 m0, m0, 0x100
	s_add_u32 s28, s28, s32
	s_addc_u32 s29, s29, 0
	global_load_lds_dword v58, s[28:29] nt
	s_add_i32 m0, m0, 0x100
	s_add_u32 s28, s28, s32
	s_addc_u32 s29, s29, 0
	global_load_lds_dword v58, s[28:29] nt
	s_add_i32 m0, m0, 0x100
	s_add_u32 s28, s28, s32
	s_addc_u32 s29, s29, 0
	global_load_lds_dword v58, s[28:29] nt
	s_mov_b64 exec, s[34:35]
	s_add_i32 m0, m0, 0x100
	s_add_u32 s28, s28, s32
	s_addc_u32 s29, s29, 0
	global_load_lds_dword v59, s[28:29] nt
	s_add_i32 m0, m0, 0x100
	s_add_u32 s28, s28, s32
	s_addc_u32 s29, s29, 0
	global_load_lds_dword v59, s[28:29] nt
	s_add_i32 m0, m0, 0x100
	s_add_u32 s28, s28, s32
	s_addc_u32 s29, s29, 0
	global_load_lds_dword v59, s[28:29] nt
	s_add_i32 m0, m0, 0x100
	s_add_u32 s28, s28, s32
	s_addc_u32 s29, s29, 0
	global_load_lds_dword v59, s[28:29] nt
	s_mov_b64 exec, s[36:37]
	s_add_i32 m0, m0, 0x100
	s_add_u32 s28, s28, s32
	s_addc_u32 s29, s29, 0
	global_load_lds_dword v60, s[28:29] nt
	s_add_i32 m0, m0, 0x100
	s_add_u32 s28, s28, s32
	s_addc_u32 s29, s29, 0
	global_load_lds_dword v60, s[28:29] nt
	s_add_i32 m0, m0, 0x100
	s_add_u32 s28, s28, s32
	s_addc_u32 s29, s29, 0
	global_load_lds_dword v60, s[28:29] nt
	s_add_i32 m0, m0, 0x100
	s_add_u32 s28, s28, s32
	s_addc_u32 s29, s29, 0
	global_load_lds_dword v60, s[28:29] nt
	s_mov_b64 exec, s[36:37]
	s_add_i32 m0, m0, 0x100
	s_add_u32 s28, s28, s32
	s_addc_u32 s29, s29, 0
	global_load_lds_dword v61, s[28:29] nt
	s_add_i32 m0, m0, 0x100
	s_add_u32 s28, s28, s32
	s_addc_u32 s29, s29, 0
	global_load_lds_dword v61, s[28:29] nt
	s_add_i32 m0, m0, 0x100
	s_add_u32 s28, s28, s32
	s_addc_u32 s29, s29, 0
	global_load_lds_dword v61, s[28:29] nt
	s_add_i32 m0, m0, 0x100
	s_add_u32 s28, s28, s32
	s_addc_u32 s29, s29, 0
	global_load_lds_dword v61, s[28:29] nt
	s_mov_b64 exec, s[34:35]
	s_add_i32 m0, m0, 0x100
	s_add_u32 s28, s28, s32
	s_addc_u32 s29, s29, 0
	global_load_lds_dword v58, s[28:29] nt
	s_add_i32 m0, m0, 0x100
	s_add_u32 s28, s28, s32
	s_addc_u32 s29, s29, 0
	global_load_lds_dword v58, s[28:29] nt
	s_add_i32 m0, m0, 0x100
	s_add_u32 s28, s28, s32
	s_addc_u32 s29, s29, 0
	global_load_lds_dword v58, s[28:29] nt
	s_add_i32 m0, m0, 0x100
	s_add_u32 s28, s28, s32
	s_addc_u32 s29, s29, 0
	global_load_lds_dword v58, s[28:29] nt
	s_mov_b64 exec, s[34:35]
	s_add_i32 m0, m0, 0x100
	s_add_u32 s28, s28, s32
	s_addc_u32 s29, s29, 0
	global_load_lds_dword v59, s[28:29] nt
	s_add_i32 m0, m0, 0x100
	s_add_u32 s28, s28, s32
	s_addc_u32 s29, s29, 0
	global_load_lds_dword v59, s[28:29] nt
	s_add_i32 m0, m0, 0x100
	s_add_u32 s28, s28, s32
	s_addc_u32 s29, s29, 0
	global_load_lds_dword v59, s[28:29] nt
	s_add_i32 m0, m0, 0x100
	s_add_u32 s28, s28, s32
	s_addc_u32 s29, s29, 0
	global_load_lds_dword v59, s[28:29] nt
	s_mov_b64 exec, s[36:37]
	s_add_i32 m0, m0, 0x100
	s_add_u32 s28, s28, s32
	s_addc_u32 s29, s29, 0
	global_load_lds_dword v60, s[28:29] nt
	s_add_i32 m0, m0, 0x100
	s_add_u32 s28, s28, s32
	s_addc_u32 s29, s29, 0
	global_load_lds_dword v60, s[28:29] nt
	s_add_i32 m0, m0, 0x100
	s_add_u32 s28, s28, s32
	s_addc_u32 s29, s29, 0
	global_load_lds_dword v60, s[28:29] nt
	s_add_i32 m0, m0, 0x100
	s_add_u32 s28, s28, s32
	s_addc_u32 s29, s29, 0
	global_load_lds_dword v60, s[28:29] nt
	s_mov_b64 exec, s[36:37]
	s_add_i32 m0, m0, 0x100
	s_add_u32 s28, s28, s32
	s_addc_u32 s29, s29, 0
	global_load_lds_dword v61, s[28:29] nt
	s_add_i32 m0, m0, 0x100
	s_add_u32 s28, s28, s32
	s_addc_u32 s29, s29, 0
	global_load_lds_dword v61, s[28:29] nt
	s_add_i32 m0, m0, 0x100
	s_add_u32 s28, s28, s32
	s_addc_u32 s29, s29, 0
	global_load_lds_dword v61, s[28:29] nt
	s_add_i32 m0, m0, 0x100
	s_add_u32 s28, s28, s32
	s_addc_u32 s29, s29, 0
	global_load_lds_dword v61, s[28:29] nt
	s_mov_b64 exec, -1
